# loop back-edge work moved before the end-of-softmax barrier; window attention issues tiles 2 and 3 LDS-DMA in the unit prologue
# speedup vs baseline: 1.0393x; 1.0006x over previous
; __device__ __forceinline__ unsigned cvtpk(float lo, float hi) { f32x2_t v = {lo, hi}; bf16x2_t b = __builtin_convertvector(v, bf16x2_t); return __builtin_bit_cast(unsigned, b); }
; #define ATT_BAR_V(full) do { if (full) { if (MODE) ATT_WAIT_BAR(4); else ATT_WAIT_BAR(2); } else ATT_WAIT_BAR(0); } while (0)
; #define ATT_BAR_L() asm volatile("s_waitcnt lgkmcnt(0)\n\ts_barrier" ::: "memory")
; template <int MODE>
; __device__ __forceinline__ void attn_unit(const Tensors& T0, int ureq, int b, int hh, int qblk, LAS3 char* shm, const bool dummy = false) {
;     ...
;     float sacc = 0.f;
; #pragma unroll
;     for (int r = 0; r < 16; ++r) { C0[r] = __builtin_amdgcn_exp2f(C0[r]); C1[r] = __builtin_amdgcn_exp2f(C1[r]); sacc += C0[r] + C1[r]; }
;     l_reg += sacc;
; #pragma unroll
;     for (int j = 0; j < 4; ++j) { pw[0][j] = cvtpk(C0[2 * j], C0[2 * j + 1]); pw[1][j] = cvtpk(C0[8 + 2 * j], C0[8 + 2 * j + 1]);
;                                   pw[2][j] = cvtpk(C1[2 * j], C1[2 * j + 1]); pw[3][j] = cvtpk(C1[8 + 2 * j], C1[8 + 2 * j + 1]); }
;     }
;     asm volatile("" : "+v"(pw[0]), "+v"(pw[1]), "+v"(pw[2]), "+v"(pw[3]), "+v"(l_reg));
;     if (grp == 0) ATT_BAR_V(i + 2 < NT); else if (i + 1 < NT) ATT_BAR_L();
;   }
.LBB0_125:
	v_exp_f32_e32 v112, v112
	v_exp_f32_e32 v160, v96
	v_exp_f32_e32 v96, v113
	v_exp_f32_e32 v97, v97
	v_exp_f32_e32 v114, v114
	v_exp_f32_e32 v98, v98
	v_exp_f32_e32 v115, v115
	v_exp_f32_e32 v99, v99
	v_add_f32_e32 v113, v160, v112
	v_exp_f32_e32 v116, v116
	v_exp_f32_e32 v100, v100
	v_add_f32_e32 v161, v97, v96
	v_exp_f32_e32 v117, v117
	v_exp_f32_e32 v101, v101
	v_add_f32_e32 v113, v161, v113
	v_add_f32_e32 v161, v98, v114
	v_exp_f32_e32 v118, v118
	v_exp_f32_e32 v102, v102
	v_add_f32_e32 v113, v161, v113
	v_add_f32_e32 v161, v99, v115
	v_exp_f32_e32 v119, v119
	v_exp_f32_e32 v103, v103
	v_add_f32_e32 v113, v161, v113
	v_add_f32_e32 v161, v100, v116
	v_exp_f32_e32 v120, v120
	v_exp_f32_e32 v104, v104
	v_add_f32_e32 v113, v161, v113
	v_add_f32_e32 v161, v101, v117
	v_exp_f32_e32 v121, v121
	v_exp_f32_e32 v105, v105
	v_add_f32_e32 v113, v161, v113
	v_add_f32_e32 v161, v102, v118
	v_exp_f32_e32 v122, v122
	v_exp_f32_e32 v106, v106
	v_add_f32_e32 v113, v161, v113
	v_add_f32_e32 v161, v103, v119
	v_exp_f32_e32 v123, v123
	v_exp_f32_e32 v107, v107
	v_add_f32_e32 v113, v161, v113
	v_add_f32_e32 v161, v104, v120
	v_exp_f32_e32 v124, v124
	v_exp_f32_e32 v108, v108
	v_add_f32_e32 v113, v161, v113
	v_add_f32_e32 v161, v105, v121
	v_exp_f32_e32 v125, v125
	v_exp_f32_e32 v109, v109
	v_add_f32_e32 v113, v161, v113
	v_add_f32_e32 v161, v106, v122
	v_exp_f32_e32 v126, v126
	v_exp_f32_e32 v110, v110
	v_add_f32_e32 v113, v161, v113
	v_add_f32_e32 v161, v107, v123
	v_exp_f32_e32 v127, v127
	v_exp_f32_e32 v111, v111
	v_add_f32_e32 v113, v161, v113
	v_add_f32_e32 v161, v108, v124
	v_add_f32_e32 v113, v161, v113
	v_add_f32_e32 v161, v109, v125
	v_add_f32_e32 v113, v161, v113
	v_add_f32_e32 v161, v110, v126
	v_add_f32_e32 v113, v161, v113
	v_add_f32_e32 v161, v111, v127
	v_add_f32_e32 v113, v161, v113
	v_cvt_pk_bf16_f32 v96, v112, v96
	v_cvt_pk_bf16_f32 v168, v120, v121
	v_cvt_pk_bf16_f32 v164, v160, v97
	v_cvt_pk_bf16_f32 v160, v104, v105
	v_cvt_pk_bf16_f32 v97, v114, v115
	v_cvt_pk_bf16_f32 v169, v122, v123
	v_cvt_pk_bf16_f32 v165, v98, v99
	v_cvt_pk_bf16_f32 v161, v106, v107
	v_cvt_pk_bf16_f32 v98, v116, v117
	v_cvt_pk_bf16_f32 v170, v124, v125
	v_cvt_pk_bf16_f32 v166, v100, v101
	v_cvt_pk_bf16_f32 v162, v108, v109
	v_cvt_pk_bf16_f32 v99, v118, v119
	v_cvt_pk_bf16_f32 v171, v126, v127
	v_cvt_pk_bf16_f32 v167, v102, v103
	v_cvt_pk_bf16_f32 v163, v110, v111
	v_add_f32_e32 v198, v198, v113
	s_add_i32 s93, s93, 1
	s_add_i32 s8, s94, s93
	s_add_i32 s95, s95, 64
	s_add_u32 s100, s100, s68
	s_addc_u32 s101, s101, s69
	v_add_u32_e32 v203, 0x100, v203
	s_mov_b32 s98, s97
	s_cmp_ge_u32 s96, s82
	s_cbranch_scc1 .Lm1_B_drain_g0
	s_waitcnt vmcnt(4) lgkmcnt(0)
	s_barrier
	s_branch .LBB0_105
.Lm1_B_drain_g0:
	s_waitcnt vmcnt(0) lgkmcnt(0)
	s_barrier
	s_cmp_eq_u32 s8, 2
	s_cbranch_scc0 .LBB0_105
	s_branch .LBB0_136

; __device__ __forceinline__ unsigned cvtpk(float lo, float hi) { f32x2_t v = {lo, hi}; bf16x2_t b = __builtin_convertvector(v, bf16x2_t); return __builtin_bit_cast(unsigned, b); }
; #define ATT_BAR_V(full) do { if (full) { if (MODE) ATT_WAIT_BAR(4); else ATT_WAIT_BAR(2); } else ATT_WAIT_BAR(0); } while (0)
; #define ATT_BAR_L() asm volatile("s_waitcnt lgkmcnt(0)\n\ts_barrier" ::: "memory")
; template <int MODE>
; __device__ __forceinline__ void attn_unit(const Tensors& T0, int ureq, int b, int hh, int qblk, LAS3 char* shm, const bool dummy = false) {
;     ...
;     float sacc = 0.f;
; #pragma unroll
;     for (int r = 0; r < 16; ++r) { C0[r] = __builtin_amdgcn_exp2f(C0[r]); C1[r] = __builtin_amdgcn_exp2f(C1[r]); sacc += C0[r] + C1[r]; }
;     l_reg += sacc;
; #pragma unroll
;     for (int j = 0; j < 4; ++j) { pw[0][j] = cvtpk(C0[2 * j], C0[2 * j + 1]); pw[1][j] = cvtpk(C0[8 + 2 * j], C0[8 + 2 * j + 1]);
;                                   pw[2][j] = cvtpk(C1[2 * j], C1[2 * j + 1]); pw[3][j] = cvtpk(C1[8 + 2 * j], C1[8 + 2 * j + 1]); }
;     }
;     asm volatile("" : "+v"(pw[0]), "+v"(pw[1]), "+v"(pw[2]), "+v"(pw[3]), "+v"(l_reg));
;     if (grp == 0) ATT_BAR_V(i + 2 < NT); else if (i + 1 < NT) ATT_BAR_L();
;   }
.Lm1g1_125:
	v_exp_f32_e32 v112, v112
	v_exp_f32_e32 v160, v96
	v_exp_f32_e32 v96, v113
	v_exp_f32_e32 v97, v97
	v_exp_f32_e32 v114, v114
	v_exp_f32_e32 v98, v98
	v_exp_f32_e32 v115, v115
	v_exp_f32_e32 v99, v99
	v_add_f32_e32 v113, v160, v112
	v_exp_f32_e32 v116, v116
	v_exp_f32_e32 v100, v100
	v_add_f32_e32 v161, v97, v96
	v_exp_f32_e32 v117, v117
	v_exp_f32_e32 v101, v101
	v_add_f32_e32 v113, v161, v113
	v_add_f32_e32 v161, v98, v114
	v_exp_f32_e32 v118, v118
	v_exp_f32_e32 v102, v102
	v_add_f32_e32 v113, v161, v113
	v_add_f32_e32 v161, v99, v115
	v_exp_f32_e32 v119, v119
	v_exp_f32_e32 v103, v103
	v_add_f32_e32 v113, v161, v113
	v_add_f32_e32 v161, v100, v116
	v_exp_f32_e32 v120, v120
	v_exp_f32_e32 v104, v104
	v_add_f32_e32 v113, v161, v113
	v_add_f32_e32 v161, v101, v117
	v_exp_f32_e32 v121, v121
	v_exp_f32_e32 v105, v105
	v_add_f32_e32 v113, v161, v113
	v_add_f32_e32 v161, v102, v118
	v_exp_f32_e32 v122, v122
	v_exp_f32_e32 v106, v106
	v_add_f32_e32 v113, v161, v113
	v_add_f32_e32 v161, v103, v119
	v_exp_f32_e32 v123, v123
	v_exp_f32_e32 v107, v107
	v_add_f32_e32 v113, v161, v113
	v_add_f32_e32 v161, v104, v120
	v_exp_f32_e32 v124, v124
	v_exp_f32_e32 v108, v108
	v_add_f32_e32 v113, v161, v113
	v_add_f32_e32 v161, v105, v121
	v_exp_f32_e32 v125, v125
	v_exp_f32_e32 v109, v109
	v_add_f32_e32 v113, v161, v113
	v_add_f32_e32 v161, v106, v122
	v_exp_f32_e32 v126, v126
	v_exp_f32_e32 v110, v110
	v_add_f32_e32 v113, v161, v113
	v_add_f32_e32 v161, v107, v123
	v_exp_f32_e32 v127, v127
	v_exp_f32_e32 v111, v111
	v_add_f32_e32 v113, v161, v113
	v_add_f32_e32 v161, v108, v124
	v_add_f32_e32 v113, v161, v113
	v_add_f32_e32 v161, v109, v125
	v_add_f32_e32 v113, v161, v113
	v_add_f32_e32 v161, v110, v126
	v_add_f32_e32 v113, v161, v113
	v_add_f32_e32 v161, v111, v127
	v_add_f32_e32 v113, v161, v113
	v_cvt_pk_bf16_f32 v96, v112, v96
	v_cvt_pk_bf16_f32 v168, v120, v121
	v_cvt_pk_bf16_f32 v164, v160, v97
	v_cvt_pk_bf16_f32 v160, v104, v105
	v_cvt_pk_bf16_f32 v97, v114, v115
	v_cvt_pk_bf16_f32 v169, v122, v123
	v_cvt_pk_bf16_f32 v165, v98, v99
	v_cvt_pk_bf16_f32 v161, v106, v107
	v_cvt_pk_bf16_f32 v98, v116, v117
	v_cvt_pk_bf16_f32 v170, v124, v125
	v_cvt_pk_bf16_f32 v166, v100, v101
	v_cvt_pk_bf16_f32 v162, v108, v109
	v_cvt_pk_bf16_f32 v99, v118, v119
	v_cvt_pk_bf16_f32 v171, v126, v127
	v_cvt_pk_bf16_f32 v167, v102, v103
	v_cvt_pk_bf16_f32 v163, v110, v111
	v_add_f32_e32 v198, v198, v113
	s_add_i32 s93, s93, 1
	s_add_i32 s8, s94, s93
	s_add_i32 s95, s95, 64
	s_add_u32 s100, s100, s68
	s_addc_u32 s101, s101, s69
	v_add_u32_e32 v203, 0x100, v203
	s_mov_b32 s98, s97
	s_cmp_ge_u32 s96, s83
	s_cbranch_scc1 .LBB0_136
	s_waitcnt lgkmcnt(0)
	s_barrier
	s_branch .Lm1g1_105

; #define ATT_BAR_V(full) do { if (full) { if (MODE) ATT_WAIT_BAR(4); else ATT_WAIT_BAR(2); } else ATT_WAIT_BAR(0); } while (0)
; #define ATT_BAR_L() asm volatile("s_waitcnt lgkmcnt(0)\n\ts_barrier" ::: "memory")
; template <int MODE>
; __device__ __forceinline__ void attn_unit(const Tensors& T0, int ureq, int b, int hh, int qblk, LAS3 char* shm, const bool dummy = false) {
;     ...
;   if (!(ATT_ABL == 2 && dummy)) { ATT_DMA(t_lo, 0); ATT_DMA(t_lo + 1, SLOTB); }
;   ATT_BAR_V(true);
;   if (grp == 1) { if (NT > 2 && !(ATT_ABL == 2 && dummy)) ATT_DMA(t_lo + 2, 2 * SLOTB); ATT_BAR_L(); }
.LBB0_156:
	s_or_b64 exec, exec, s[46:47]
	s_and_b32 s82, s19, s37
	s_and_b32 s19, s39, 3
	s_ashr_i32 s39, s38, 31
	s_ashr_i32 s37, s81, 6
	s_lshl_b64 s[46:47], s[38:39], 13
	s_add_u32 s46, s46, 0x8000
	s_addc_u32 s47, s47, 0
	s_lshl_b64 s[38:39], s[38:39], 12
	s_and_b64 s[4:5], s[4:5], exec
	s_cselect_b32 s5, s39, s47
	s_cselect_b32 s4, s38, s46
	s_lshl_b32 s38, s37, 5
	s_lshl_b32 s46, s82, 6
	s_and_b32 s38, s38, 32
	s_ashr_i32 s84, s81, 7
	s_or_b32 s85, s38, s46
	s_add_u32 s54, s4, s85
	s_addc_u32 s55, s5, 0
	s_lshl_b64 s[38:39], s[54:55], 11
	s_add_u32 s47, s44, s38
	s_addc_u32 s39, s45, s39
	s_lshl_b32 s38, s19, 2
	s_add_i32 s38, s84, s38
	s_lshl_b32 s44, s38, 6
	s_ashr_i32 s45, s44, 31
	s_lshl_b64 s[66:67], s[44:45], 1
	s_add_u32 s44, s47, s66
	s_addc_u32 s45, s39, s67
	s_lshl_b64 s[4:5], s[4:5], 10
	s_add_u32 s4, s42, s4
	s_addc_u32 s5, s43, s5
	s_lshl_b32 s19, s19, 7
	s_add_u32 s4, s4, s19
	s_addc_u32 s5, s5, 0
	s_ashr_i32 s39, s38, 31
	v_and_b32_e32 v123, 31, v16
	s_lshl_b64 s[38:39], s[38:39], 2
	v_bfe_u32 v122, v16, 5, 1
	s_add_u32 s38, s40, s38
	v_lshlrev_b32_e32 v0, 11, v123
	s_addc_u32 s39, s41, s39
	v_lshl_or_b32 v0, v122, 4, v0
	v_mov_b64_e32 v[2:3], s[38:39]
	v_lshl_add_u64 v[14:15], s[44:45], 0, v[0:1]
	global_load_dword v17, v[2:3], off
	s_nop 0
	global_load_dwordx4 v[2:5], v[14:15], off
	global_load_dwordx4 v[6:9], v[14:15], off offset:32
	global_load_dwordx4 v[10:13], v[14:15], off offset:64
	global_load_dwordx4 v[96:99], v[14:15], off offset:96
	v_bfe_u32 v18, v16, 3, 3
	v_lshl_or_b32 v14, s37, 3, v18
	v_ashrrev_i32_e32 v15, 31, v14
	v_lshlrev_b64 v[20:21], 10, v[14:15]
	v_lshrrev_b32_e32 v0, 1, v14
	v_lshl_add_u64 v[22:23], s[4:5], 0, v[20:21]
	v_xor_b32_e32 v0, v0, v16
	s_add_i32 s4, s46, 0xffffff80
	s_addk_i32 s46, 0xc0
	v_lshlrev_b32_e32 v0, 4, v0
	s_lshl_b32 s80, s37, 10
	s_min_u32 s5, s46, s18
	v_and_b32_e32 v0, 0x70, v0
	v_lshrrev_b32_e32 v21, 2, v16
	v_lshrrev_b32_e32 v20, 4, v16
	s_add_i32 s80, s80, 0
	s_ashr_i32 s4, s4, 6
	s_lshr_b32 s83, s5, 6
	v_lshl_add_u64 v[14:15], v[22:23], 0, v[0:1]
	v_xor_b32_e32 v0, v21, v20
	s_cmp_gt_u32 s82, 1
	v_lshlrev_b32_e32 v19, 3, v16
	v_lshlrev_b32_e32 v0, 6, v0
	s_cselect_b32 s68, s4, 0
	v_and_b32_e32 v19, 24, v19
	v_and_b32_e32 v0, 64, v0
	s_ashr_i32 s69, s68, 31
	v_lshl_add_u64 v[22:23], v[22:23], 0, v[0:1]
	v_lshlrev_b32_e32 v0, 1, v19
	s_lshl_b64 s[4:5], s[68:69], 16
	v_lshl_add_u64 v[120:121], v[22:23], 0, v[0:1]
	v_lshl_add_u64 v[22:23], v[14:15], 0, s[4:5]
	s_mov_b32 s18, m0
	s_mov_b32 m0, s80
	s_nop 0
	global_load_lds_dwordx4 v[22:23], off
	s_mov_b32 m0, s18
	s_sub_i32 s79, s83, s68
	s_add_i32 s18, s80, 0x4000
	v_lshl_add_u64 v[22:23], v[120:121], 0, s[4:5]
	s_add_u32 s4, s4, 0x10000
	v_lshl_add_u64 v[22:23], v[22:23], 0, s[8:9]
	s_addc_u32 s5, s5, 0
	s_mov_b32 s19, m0
	s_mov_b32 m0, s18
	s_nop 0
	global_load_lds_dwordx4 v[22:23], off
	s_mov_b32 m0, s19
	v_lshl_add_u64 v[22:23], v[14:15], 0, s[4:5]
	s_add_i32 s18, s80, 0x8000
	s_mov_b32 s19, m0
	s_mov_b32 m0, s18
	s_nop 0
	global_load_lds_dwordx4 v[22:23], off
	s_mov_b32 m0, s19
	v_lshl_add_u64 v[22:23], v[120:121], 0, s[4:5]
	s_add_i32 s4, s80, 0xc000
	v_lshl_add_u64 v[22:23], v[22:23], 0, s[8:9]
	s_mov_b32 s5, m0
	s_mov_b32 m0, s4
	s_nop 0
	global_load_lds_dwordx4 v[22:23], off
	s_mov_b32 m0, s5
	s_add_i32 s4, s68, 2
	s_mov_b32 s5, 0
	s_lshl_b64 s[4:5], s[4:5], 16
	v_lshl_add_u64 v[22:23], v[14:15], 0, s[4:5]
	s_add_i32 s18, s80, 0x10000
	s_mov_b32 m0, s18
	s_nop 0
	global_load_lds_dwordx4 v[22:23], off
	v_lshl_add_u64 v[22:23], v[120:121], 0, s[4:5]
	v_lshl_add_u64 v[22:23], v[22:23], 0, s[8:9]
	s_add_i32 s18, s80, 0x14000
	s_mov_b32 m0, s18
	s_nop 0
	global_load_lds_dwordx4 v[22:23], off
	s_cmp_lt_i32 s79, 4
	s_cbranch_scc1 .Lm0_early_done
	s_add_i32 s4, s68, 3
	s_mov_b32 s5, 0
	s_lshl_b64 s[4:5], s[4:5], 16
	v_lshl_add_u64 v[22:23], v[14:15], 0, s[4:5]
	s_add_i32 s18, s80, 0x18000
	s_mov_b32 m0, s18
	s_nop 0
	global_load_lds_dwordx4 v[22:23], off
	v_lshl_add_u64 v[22:23], v[120:121], 0, s[4:5]
	v_lshl_add_u64 v[22:23], v[22:23], 0, s[8:9]
	s_add_i32 s18, s80, 0x1c000
	s_mov_b32 m0, s18
	s_nop 0
	global_load_lds_dwordx4 v[22:23], off
.Lm0_early_done:
	s_and_b32 s4, s81, 0xffffff00
	s_waitcnt vmcnt(0) lgkmcnt(0)
	s_barrier
	s_cmpk_eq_i32 s4, 0x100
	s_cselect_b64 s[70:71], -1, 0
	s_and_b64 vcc, exec, s[70:71]
	s_cbranch_vccz .LBB0_160
	s_branch .LBB0_159
	s_add_i32 s4, s68, 2
	s_mov_b32 s5, s36
	s_lshl_b64 s[4:5], s[4:5], 16
	v_lshl_add_u64 v[22:23], v[14:15], 0, s[4:5]
	s_add_i32 s18, s80, 0x10000
	s_mov_b32 s19, m0
	s_mov_b32 m0, s18
	s_nop 0
	global_load_lds_dwordx4 v[22:23], off
	s_mov_b32 m0, s19
	v_lshl_add_u64 v[22:23], v[120:121], 0, s[4:5]
	v_lshl_add_u64 v[22:23], v[22:23], 0, s[8:9]
	s_add_i32 s4, s80, 0x14000
	s_mov_b32 s5, m0
	s_mov_b32 m0, s4
	s_nop 0
	global_load_lds_dwordx4 v[22:23], off
	s_mov_b32 m0, s5

; #define ATT_SB() __builtin_amdgcn_sched_barrier(0)
; #define ATT_VREAD(buf, ks, vso) do { _Pragma("unroll") for (int d0 = 0; d0 < ND; ++d0) { const lds_cptr vq_ = ((d0 & 1) ? vpo : vpe) + (vso) + (d0 >> 1) * 8192 + (ks) * 2048; \
;       const s16x4 lo = vtr(vq_), hi4 = vtr(vq_ + 1024); \
;       buf[d0] = (bf16x8){lo[0], lo[1], lo[2], lo[3], hi4[0], hi4[1], hi4[2], hi4[3]}; } } while (0)
; template <int MODE>
; __device__ __forceinline__ void attn_unit(const Tensors& T0, int ureq, int b, int hh, int qblk, LAS3 char* shm, const bool dummy = false) {
;     ...
;     if (i == 0) asm volatile("s_nop 15\n\ts_nop 7" : "+v"(C0), "+v"(C1));
;     else asm volatile("" : "+v"(C0), "+v"(C1));
;     ATT_VREAD(vA, 0, (i & 3) * SLOTB); ATT_SB();
;     if (grp == 0 && i + 2 < NT && !(ATT_ABL == 2 && dummy)) ATT_DMA(t + 2, ((i + 2) & 3) * SLOTB);
;     if (grp == 1 && i + 3 < NT && !(ATT_ABL == 2 && dummy)) ATT_DMA(t + 3, ((i + 3) & 3) * SLOTB);
.LBB0_169:
	s_nop 15
	s_nop 7
	ds_read_b64_tr_b16 v[104:105], v127 offset:16384
	ds_read_b64_tr_b16 v[106:107], v127 offset:17408
	ds_read_b64_tr_b16 v[100:101], v126 offset:16384
	ds_read_b64_tr_b16 v[102:103], v126 offset:17408
	s_cmp_lt_u32 s79, 3
	s_cselect_b64 s[38:39], -1, 0
	s_cmp_gt_u32 s79, 2
	s_cselect_b64 s[18:19], -1, 0
	s_and_b64 s[18:19], s[72:73], s[18:19]
	s_branch .LBB0_171
	s_add_i32 s18, s68, 2
	s_mov_b32 s19, s36
	s_lshl_b64 s[18:19], s[18:19], 16
	v_lshl_add_u64 v[82:83], v[14:15], 0, s[18:19]
	s_add_i32 s37, s80, 0x10000
	s_mov_b32 s40, m0
	s_mov_b32 m0, s37
	s_nop 0
	global_load_lds_dwordx4 v[82:83], off
	s_mov_b32 m0, s40
	v_lshl_add_u64 v[82:83], v[120:121], 0, s[18:19]
	v_lshl_add_u64 v[82:83], v[82:83], 0, s[8:9]
	s_add_i32 s18, s80, 0x14000
	s_mov_b32 s19, m0
	s_mov_b32 m0, s18
	s_nop 0
	global_load_lds_dwordx4 v[82:83], off
	s_mov_b32 m0, s19
.LBB0_171:
	s_cmp_gt_u32 s79, 3
	s_cselect_b64 s[18:19], -1, 0
	s_and_b64 s[18:19], s[70:71], s[18:19]
	s_branch .LBB0_173
	s_add_i32 s18, s68, 3
	s_mov_b32 s19, s36
	s_lshl_b64 s[18:19], s[18:19], 16
	v_lshl_add_u64 v[82:83], v[14:15], 0, s[18:19]
	s_add_i32 s37, s80, 0x18000
	s_mov_b32 s40, m0
	s_mov_b32 m0, s37
	s_nop 0
	global_load_lds_dwordx4 v[82:83], off
	s_mov_b32 m0, s40
	v_lshl_add_u64 v[82:83], v[120:121], 0, s[18:19]
	v_lshl_add_u64 v[82:83], v[82:83], 0, s[8:9]
	s_add_i32 s18, s80, 0x1c000
	s_mov_b32 s19, m0
	s_mov_b32 m0, s18
	s_nop 0
	global_load_lds_dwordx4 v[82:83], off
	s_mov_b32 m0, s19

; #define ATT_SB() __builtin_amdgcn_sched_barrier(0)
; #define ATT_VREAD(buf, ks, vso) do { _Pragma("unroll") for (int d0 = 0; d0 < ND; ++d0) { const lds_cptr vq_ = ((d0 & 1) ? vpo : vpe) + (vso) + (d0 >> 1) * 8192 + (ks) * 2048; \
;       const s16x4 lo = vtr(vq_), hi4 = vtr(vq_ + 1024); \
;       buf[d0] = (bf16x8){lo[0], lo[1], lo[2], lo[3], hi4[0], hi4[1], hi4[2], hi4[3]}; } } while (0)
; template <int MODE>
; __device__ __forceinline__ void attn_unit(const Tensors& T0, int ureq, int b, int hh, int qblk, LAS3 char* shm, const bool dummy = false) {
;     ...
;     ATT_VREAD(vA, 0, (i & 3) * SLOTB); ATT_SB();
;     if (grp == 0 && i + 2 < NT && !(ATT_ABL == 2 && dummy)) ATT_DMA(t + 2, ((i + 2) & 3) * SLOTB);
;     if (grp == 1 && i + 3 < NT && !(ATT_ABL == 2 && dummy)) ATT_DMA(t + 3, ((i + 3) & 3) * SLOTB);
.LBB0_199:
	v_add_u32_e32 v100, s19, v127
	v_add_u32_e32 v102, s19, v126
	ds_read_b64_tr_b16 v[104:105], v100 offset:16384
	ds_read_b64_tr_b16 v[106:107], v100 offset:17408
	ds_read_b64_tr_b16 v[100:101], v102 offset:16384
	ds_read_b64_tr_b16 v[102:103], v102 offset:17408
	s_andn2_b64 vcc, exec, s[72:73]
	s_cbranch_vccnz .LBB0_202
	s_cmp_lt_i32 s42, 4
	s_cbranch_scc1 .LBB0_202
	s_cmp_ge_i32 s42, s79
	s_cbranch_scc1 .LBB0_202
	s_add_i32 s38, s68, s42
	s_ashr_i32 s39, s38, 31
	s_lshl_b64 s[38:39], s[38:39], 16
	v_lshl_add_u64 v[108:109], v[14:15], 0, s[38:39]
	s_and_b32 s19, s45, 0x18000
	s_add_i32 s19, s19, s80
	s_mov_b32 s45, m0
	s_mov_b32 m0, s19
	s_nop 0
	global_load_lds_dwordx4 v[108:109], off
	s_mov_b32 m0, s45
	v_lshl_add_u64 v[108:109], v[120:121], 0, s[38:39]
	v_lshl_add_u64 v[108:109], v[108:109], 0, s[8:9]
	s_addk_i32 s19, 0x4000
	s_mov_b32 s38, m0
	s_mov_b32 m0, s19
	s_nop 0
	global_load_lds_dwordx4 v[108:109], off
	s_mov_b32 m0, s38
